# re-measure v057_gufuse_nopk
# speedup vs baseline: 1.0068x; 1.0068x over previous
; #define PG8_STAGE(bufoff, gbase, voff) do { _Pragma("unroll") for (int _i = 0; _i < 2; ++_i) \
;         __builtin_amdgcn_global_load_lds((const unsigned*)((const char*)(gbase) + (voff)[_i]), (LAS unsigned*)(lds + (bufoff) + ldsw + _i * 8192), 16, 0, 0); } while (0)
; #define PG8_LDA(dst, b, h) do { _Pragma("unroll") for (int m = 0; m < 4; ++m) _Pragma("unroll") for (int k = 0; k < 2; ++k) dst[m][k] = *(const LAS bf16x8*)(lds + PG8_SA(b, h) + aoff + m * 2048 + k * 1024); } while (0)
; #define PG8_LDB(dst, b, h) do { _Pragma("unroll") for (int n = 0; n < 2; ++n) _Pragma("unroll") for (int k = 0; k < 2; ++k) dst[n][k] = *(const LAS bf16x8*)(lds + PG8_SB(b, h) + boff + n * 2048 + k * 1024); } while (0)
; #define PG8_MMA(ai, bj, At, Bt) do { __builtin_amdgcn_s_setprio(1); _Pragma("unroll") for (int k = 0; k < 2; ++k) _Pragma("unroll") for (int m = 0; m < 4; ++m) _Pragma("unroll") for (int n = 0; n < 2; ++n) \
;         acc[ai][bj][m][n] = __builtin_amdgcn_mfma_f32_16x16x32_bf16(Bt[n][k], At[m][k], acc[ai][bj][m][n], 0, 0, 0); __builtin_amdgcn_s_setprio(0); } while (0)
; #define PG8_WAIT_V(n) asm volatile("s_waitcnt vmcnt(" #n ")" ::: "memory")
; #define PG8_WAIT_L(n) asm volatile("s_waitcnt lgkmcnt(" #n ")" ::: "memory")
; #define PG8_BAR __builtin_amdgcn_s_barrier()
; #define PG8_SCHED __builtin_amdgcn_sched_barrier(0)
; template <class Epi, bool ALIGN_EPI>
; __device__ __forceinline__ void gemm_phase(LAS unsigned char* lds, const Gemm g, const StaticOrder& S, const Epi& E, const int tid) {
;     ...
;         for (int t = 0; t < nt; t += 2) {
;             const bool last = (t == nt - 2);
;             const char* a1 = cA + (size_t)(t + 1) * kstep;
;             const char* a2 = last ? nA : cA + (size_t)(t + 2) * kstep; const char* b2 = last ? nB : cB + (size_t)(t + 2) * kstep;
;             const char* a3 = a2 + kstep; const char* b3 = b2 + kstep;
;             PG8_LDB(B0, 0, 0); PG8_LDB(B1, 0, 1); PG8_SCHED; PG8_LDA(At, 0, 0); PG8_STAGE(PG8_SA(1, 1), a1 + hA, voffA);
;             PG8_WAIT_V(8); PG8_WAIT_L(0); PG8_BAR; PG8_MMA(0, 0, At, B0); PG8_MMA(0, 1, At, B1); PG8_BAR; PG8_SCHED;
;             PG8_LDA(At, 0, 1); PG8_STAGE(PG8_SB(0, 0), b2, voffB); PG8_STAGE(PG8_SB(0, 1), b2 + hB, voffB); PG8_STAGE(PG8_SA(0, 0), a2, voffA);
;             PG8_WAIT_V(8); PG8_WAIT_L(0); PG8_BAR; PG8_MMA(1, 0, At, B0); PG8_MMA(1, 1, At, B1); PG8_BAR; PG8_SCHED;
.Lgu_last:
	s_add_i32 s11, s10, 2
	s_cmp_eq_u32 s58, s10
	v_lshl_add_u64 v[146:147], v[142:143], 0, s[92:93]
	s_cselect_b64 vcc, -1, 0
	v_add_u32_e32 v150, s33, v151
	s_add_i32 s10, 0, 0x14000
	v_cndmask_b32_e32 v167, v147, v139, vcc
	v_cndmask_b32_e32 v166, v146, v138, vcc
	ds_read_b128 v[146:149], v150
	ds_read_b128 v[154:157], v150 offset:1024
	ds_read_b128 v[158:161], v150 offset:2048
	ds_read_b128 v[162:165], v150 offset:3072
	v_add_u32_e32 v150, s10, v151
	ds_read_b128 v[176:179], v150
	ds_read_b128 v[180:183], v150 offset:1024
	ds_read_b128 v[184:187], v150 offset:2048
	ds_read_b128 v[188:191], v150 offset:3072
	v_cndmask_b32_e32 v221, v145, v141, vcc
	v_cndmask_b32_e32 v220, v144, v140, vcc
	v_lshl_add_u64 v[226:227], v[142:143], 0, v[134:135]
	s_add_i32 m0, s51, 0xc000
	ds_read_b128 v[192:195], v153
	ds_read_b128 v[196:199], v153 offset:1024
	ds_read_b128 v[200:203], v153 offset:2048
	ds_read_b128 v[204:207], v153 offset:3072
	ds_read_b128 v[208:211], v153 offset:4096
	ds_read_b128 v[212:215], v153 offset:5120
	ds_read_b128 v[216:219], v153 offset:6144
	ds_read_b128 v[240:243], v153 offset:7168
	global_load_lds_dwordx4 v[226:227], off
	v_lshl_add_u64 v[226:227], v[142:143], 0, v[136:137]
	s_add_i32 m0, s51, 0xe000
	s_nop 0
	global_load_lds_dwordx4 v[226:227], off
	s_waitcnt vmcnt(8)
	s_waitcnt lgkmcnt(0)
	s_barrier
	s_setprio 1
	s_waitcnt lgkmcnt(0)
	v_mfma_f32_16x16x32_bf16 v[120:123], v[146:149], v[192:195], v[120:123]
	v_mfma_f32_16x16x32_bf16 v[112:115], v[158:161], v[192:195], v[112:115]
	v_mfma_f32_16x16x32_bf16 v[104:107], v[146:149], v[200:203], v[104:107]
	v_mfma_f32_16x16x32_bf16 v[96:99], v[158:161], v[200:203], v[96:99]
	v_mfma_f32_16x16x32_bf16 v[88:91], v[146:149], v[208:211], v[88:91]
	v_mfma_f32_16x16x32_bf16 v[80:83], v[158:161], v[208:211], v[80:83]
	v_mfma_f32_16x16x32_bf16 v[72:75], v[146:149], v[216:219], v[72:75]
	v_mfma_f32_16x16x32_bf16 v[64:67], v[158:161], v[216:219], v[64:67]
	v_mfma_f32_16x16x32_bf16 v[120:123], v[154:157], v[196:199], v[120:123]
	v_mfma_f32_16x16x32_bf16 v[112:115], v[162:165], v[196:199], v[112:115]
	v_mfma_f32_16x16x32_bf16 v[104:107], v[154:157], v[204:207], v[104:107]
	v_mfma_f32_16x16x32_bf16 v[96:99], v[162:165], v[204:207], v[96:99]
	v_mfma_f32_16x16x32_bf16 v[88:91], v[154:157], v[212:215], v[88:91]
	v_mfma_f32_16x16x32_bf16 v[80:83], v[162:165], v[212:215], v[80:83]
	v_mfma_f32_16x16x32_bf16 v[72:75], v[154:157], v[240:243], v[72:75]
	v_mfma_f32_16x16x32_bf16 v[64:67], v[162:165], v[240:243], v[64:67]
	s_setprio 0
	s_setprio 1
	v_mfma_f32_16x16x32_bf16 v[124:127], v[176:179], v[192:195], v[124:127]
	v_mfma_f32_16x16x32_bf16 v[116:119], v[184:187], v[192:195], v[116:119]
	v_mfma_f32_16x16x32_bf16 v[108:111], v[176:179], v[200:203], v[108:111]
	v_mfma_f32_16x16x32_bf16 v[100:103], v[184:187], v[200:203], v[100:103]
	v_mfma_f32_16x16x32_bf16 v[92:95], v[176:179], v[208:211], v[92:95]
	v_mfma_f32_16x16x32_bf16 v[84:87], v[184:187], v[208:211], v[84:87]
	v_mfma_f32_16x16x32_bf16 v[76:79], v[176:179], v[216:219], v[76:79]
	v_mfma_f32_16x16x32_bf16 v[68:71], v[184:187], v[216:219], v[68:71]
	v_mfma_f32_16x16x32_bf16 v[124:127], v[180:183], v[196:199], v[124:127]
	v_mfma_f32_16x16x32_bf16 v[116:119], v[188:191], v[196:199], v[116:119]
	v_mfma_f32_16x16x32_bf16 v[108:111], v[180:183], v[204:207], v[108:111]
	v_mfma_f32_16x16x32_bf16 v[100:103], v[188:191], v[204:207], v[100:103]
	v_mfma_f32_16x16x32_bf16 v[92:95], v[180:183], v[212:215], v[92:95]
	v_mfma_f32_16x16x32_bf16 v[84:87], v[188:191], v[212:215], v[84:87]
	v_mfma_f32_16x16x32_bf16 v[76:79], v[180:183], v[240:243], v[76:79]
	v_mfma_f32_16x16x32_bf16 v[68:71], v[188:191], v[240:243], v[68:71]
	s_setprio 0
	s_barrier
	s_add_i32 s65, s33, s45
	v_lshl_add_u64 v[226:227], v[220:221], 0, v[168:169]
	s_mov_b32 m0, s65
	ds_read_b128 v[192:195], v153 offset:16384
	ds_read_b128 v[196:199], v153 offset:17408
	ds_read_b128 v[200:203], v153 offset:18432
	ds_read_b128 v[204:207], v153 offset:19456
	ds_read_b128 v[208:211], v153 offset:20480
	ds_read_b128 v[212:215], v153 offset:21504
	ds_read_b128 v[216:219], v153 offset:22528
	ds_read_b128 v[240:243], v153 offset:23552
	global_load_lds_dwordx4 v[226:227], off
	v_lshl_add_u64 v[244:245], v[220:221], 0, v[128:129]
	s_add_i32 m0, s65, 0x2000
	v_lshl_add_u64 v[220:221], v[220:221], 0, s[12:13]
	s_add_i32 s10, s10, s45
	global_load_lds_dwordx4 v[244:245], off
	v_lshl_add_u64 v[246:247], v[220:221], 0, v[168:169]
	s_mov_b32 m0, s10
	v_lshl_add_u64 v[220:221], v[220:221], 0, v[128:129]
	global_load_lds_dwordx4 v[246:247], off
	s_add_i32 m0, s10, 0x2000
	v_lshl_add_u64 v[248:249], v[166:167], 0, v[132:133]
	global_load_lds_dwordx4 v[220:221], off
	s_mov_b32 m0, s51
	v_lshl_add_u64 v[250:251], v[166:167], 0, v[130:131]
	global_load_lds_dwordx4 v[248:249], off
	s_mov_b32 m0, s52
	s_nop 0
	global_load_lds_dwordx4 v[250:251], off
	s_waitcnt vmcnt(8)
	s_waitcnt lgkmcnt(0)
	s_barrier
; #define PG8_STAGE(bufoff, gbase, voff) do { _Pragma("unroll") for (int _i = 0; _i < 2; ++_i) \
;         __builtin_amdgcn_global_load_lds((const unsigned*)((const char*)(gbase) + (voff)[_i]), (LAS unsigned*)(lds + (bufoff) + ldsw + _i * 8192), 16, 0, 0); } while (0)
; #define PG8_LDA(dst, b, h) do { _Pragma("unroll") for (int m = 0; m < 4; ++m) _Pragma("unroll") for (int k = 0; k < 2; ++k) dst[m][k] = *(const LAS bf16x8*)(lds + PG8_SA(b, h) + aoff + m * 2048 + k * 1024); } while (0)
; #define PG8_LDB(dst, b, h) do { _Pragma("unroll") for (int n = 0; n < 2; ++n) _Pragma("unroll") for (int k = 0; k < 2; ++k) dst[n][k] = *(const LAS bf16x8*)(lds + PG8_SB(b, h) + boff + n * 2048 + k * 1024); } while (0)
; #define PG8_MMA(ai, bj, At, Bt) do { __builtin_amdgcn_s_setprio(1); _Pragma("unroll") for (int k = 0; k < 2; ++k) _Pragma("unroll") for (int m = 0; m < 4; ++m) _Pragma("unroll") for (int n = 0; n < 2; ++n) \
;         acc[ai][bj][m][n] = __builtin_amdgcn_mfma_f32_16x16x32_bf16(Bt[n][k], At[m][k], acc[ai][bj][m][n], 0, 0, 0); __builtin_amdgcn_s_setprio(0); } while (0)
; #define PG8_WAIT_V(n) asm volatile("s_waitcnt vmcnt(" #n ")" ::: "memory")
; #define PG8_WAIT_L(n) asm volatile("s_waitcnt lgkmcnt(" #n ")" ::: "memory")
; #define PG8_BAR __builtin_amdgcn_s_barrier()
; #define PG8_SCHED __builtin_amdgcn_sched_barrier(0)
; template <class Epi, bool ALIGN_EPI>
; __device__ __forceinline__ void gemm_phase(LAS unsigned char* lds, const Gemm g, const StaticOrder& S, const Epi& E, const int tid) {
;     ...
;             PG8_WAIT_V(8); PG8_WAIT_L(0); PG8_BAR; PG8_MMA(1, 0, At, B0); PG8_MMA(1, 1, At, B1); PG8_BAR; PG8_SCHED;
;             PG8_LDB(B0, 1, 0); PG8_LDB(B1, 1, 1); PG8_SCHED; PG8_LDA(At, 1, 0); PG8_STAGE(PG8_SA(0, 1), a2 + hA, voffA);
;             PG8_WAIT_V(8); PG8_WAIT_L(0); PG8_BAR; PG8_MMA(0, 0, At, B0); PG8_MMA(0, 1, At, B1); PG8_BAR; PG8_SCHED;
;             PG8_LDA(At, 1, 1); PG8_STAGE(PG8_SB(1, 0), b3, voffB); PG8_STAGE(PG8_SB(1, 1), b3 + hB, voffB); PG8_STAGE(PG8_SA(1, 0), a3, voffA);
;             PG8_WAIT_V(8); PG8_WAIT_L(0); PG8_BAR; PG8_MMA(1, 0, At, B0); PG8_MMA(1, 1, At, B1); PG8_BAR; PG8_SCHED;
	s_setprio 1
	s_waitcnt lgkmcnt(0)
	v_mfma_f32_16x16x32_bf16 v[56:59], v[146:149], v[192:195], v[56:59]
	v_mfma_f32_16x16x32_bf16 v[48:51], v[158:161], v[192:195], v[48:51]
	v_mfma_f32_16x16x32_bf16 v[40:43], v[146:149], v[200:203], v[40:43]
	v_mfma_f32_16x16x32_bf16 v[32:35], v[158:161], v[200:203], v[32:35]
	v_mfma_f32_16x16x32_bf16 v[24:27], v[146:149], v[208:211], v[24:27]
	v_mfma_f32_16x16x32_bf16 v[16:19], v[158:161], v[208:211], v[16:19]
	v_mfma_f32_16x16x32_bf16 v[8:11], v[146:149], v[216:219], v[8:11]
	v_mfma_f32_16x16x32_bf16 v[4:7], v[158:161], v[216:219], v[4:7]
	v_mfma_f32_16x16x32_bf16 v[56:59], v[154:157], v[196:199], v[56:59]
	v_mfma_f32_16x16x32_bf16 v[48:51], v[162:165], v[196:199], v[48:51]
	v_mfma_f32_16x16x32_bf16 v[40:43], v[154:157], v[204:207], v[40:43]
	v_mfma_f32_16x16x32_bf16 v[32:35], v[162:165], v[204:207], v[32:35]
	v_mfma_f32_16x16x32_bf16 v[24:27], v[154:157], v[212:215], v[24:27]
	v_mfma_f32_16x16x32_bf16 v[16:19], v[162:165], v[212:215], v[16:19]
	v_mfma_f32_16x16x32_bf16 v[8:11], v[154:157], v[240:243], v[8:11]
	v_mfma_f32_16x16x32_bf16 v[4:7], v[162:165], v[240:243], v[4:7]
	s_setprio 0
	s_setprio 1
	v_mfma_f32_16x16x32_bf16 v[60:63], v[176:179], v[192:195], v[60:63]
	v_mfma_f32_16x16x32_bf16 v[52:55], v[184:187], v[192:195], v[52:55]
	v_mfma_f32_16x16x32_bf16 v[44:47], v[176:179], v[200:203], v[44:47]
	v_mfma_f32_16x16x32_bf16 v[36:39], v[184:187], v[200:203], v[36:39]
	v_mfma_f32_16x16x32_bf16 v[28:31], v[176:179], v[208:211], v[28:31]
	v_mfma_f32_16x16x32_bf16 v[20:23], v[184:187], v[208:211], v[20:23]
	v_mfma_f32_16x16x32_bf16 v[12:15], v[176:179], v[216:219], v[12:15]
	v_mfma_f32_16x16x32_bf16 v[0:3], v[184:187], v[216:219], v[0:3]
	v_mfma_f32_16x16x32_bf16 v[60:63], v[180:183], v[196:199], v[60:63]
	v_mfma_f32_16x16x32_bf16 v[52:55], v[188:191], v[196:199], v[52:55]
	v_mfma_f32_16x16x32_bf16 v[44:47], v[180:183], v[204:207], v[44:47]
	v_mfma_f32_16x16x32_bf16 v[36:39], v[188:191], v[204:207], v[36:39]
	v_mfma_f32_16x16x32_bf16 v[28:31], v[180:183], v[212:215], v[28:31]
	v_mfma_f32_16x16x32_bf16 v[20:23], v[188:191], v[212:215], v[20:23]
	v_mfma_f32_16x16x32_bf16 v[12:15], v[180:183], v[240:243], v[12:15]
	v_mfma_f32_16x16x32_bf16 v[0:3], v[188:191], v[240:243], v[0:3]
	s_setprio 0
	s_barrier
	s_add_i32 s10, 0, 0x18000
	v_add_u32_e32 v150, s10, v151
	s_add_i32 s65, 0, 0x1c000
	ds_read_b128 v[146:149], v150
	ds_read_b128 v[154:157], v150 offset:1024
	ds_read_b128 v[158:161], v150 offset:2048
	ds_read_b128 v[162:165], v150 offset:3072
	v_add_u32_e32 v150, s65, v151
	ds_read_b128 v[176:179], v150
	ds_read_b128 v[180:183], v150 offset:1024
	ds_read_b128 v[184:187], v150 offset:2048
	ds_read_b128 v[188:191], v150 offset:3072
	v_lshl_add_u64 v[166:167], v[166:167], 0, s[94:95]
	s_mov_b32 m0, s53
	v_lshl_add_u64 v[252:253], v[166:167], 0, v[132:133]
	ds_read_b128 v[192:195], v153 offset:32768
	ds_read_b128 v[196:199], v153 offset:33792
	ds_read_b128 v[200:203], v153 offset:34816
	ds_read_b128 v[204:207], v153 offset:35840
	ds_read_b128 v[208:211], v153 offset:36864
	ds_read_b128 v[212:215], v153 offset:37888
	ds_read_b128 v[216:219], v153 offset:38912
	ds_read_b128 v[240:243], v153 offset:39936
	global_load_lds_dwordx4 v[252:253], off
	v_lshl_add_u64 v[166:167], v[166:167], 0, v[130:131]
	s_mov_b32 m0, s54
	s_nop 0
	global_load_lds_dwordx4 v[166:167], off
	s_waitcnt vmcnt(8)
	s_waitcnt lgkmcnt(0)
	s_barrier
	s_setprio 1
	s_waitcnt lgkmcnt(0)
	v_mfma_f32_16x16x32_bf16 v[120:123], v[146:149], v[192:195], v[120:123]
	v_mfma_f32_16x16x32_bf16 v[112:115], v[158:161], v[192:195], v[112:115]
	v_mfma_f32_16x16x32_bf16 v[104:107], v[146:149], v[200:203], v[104:107]
	v_mfma_f32_16x16x32_bf16 v[96:99], v[158:161], v[200:203], v[96:99]
	v_mfma_f32_16x16x32_bf16 v[88:91], v[146:149], v[208:211], v[88:91]
	v_mfma_f32_16x16x32_bf16 v[80:83], v[158:161], v[208:211], v[80:83]
	v_mfma_f32_16x16x32_bf16 v[72:75], v[146:149], v[216:219], v[72:75]
	v_mfma_f32_16x16x32_bf16 v[64:67], v[158:161], v[216:219], v[64:67]
	v_mfma_f32_16x16x32_bf16 v[120:123], v[154:157], v[196:199], v[120:123]
	v_mfma_f32_16x16x32_bf16 v[112:115], v[162:165], v[196:199], v[112:115]
	v_mfma_f32_16x16x32_bf16 v[104:107], v[154:157], v[204:207], v[104:107]
	v_mfma_f32_16x16x32_bf16 v[96:99], v[162:165], v[204:207], v[96:99]
	v_mfma_f32_16x16x32_bf16 v[88:91], v[154:157], v[212:215], v[88:91]
	v_mfma_f32_16x16x32_bf16 v[80:83], v[162:165], v[212:215], v[80:83]
	v_mfma_f32_16x16x32_bf16 v[72:75], v[154:157], v[240:243], v[72:75]
	v_mfma_f32_16x16x32_bf16 v[64:67], v[162:165], v[240:243], v[64:67]
	s_setprio 0
	s_setprio 1
	v_mfma_f32_16x16x32_bf16 v[124:127], v[176:179], v[192:195], v[124:127]
	v_mfma_f32_16x16x32_bf16 v[116:119], v[184:187], v[192:195], v[116:119]
	v_mfma_f32_16x16x32_bf16 v[108:111], v[176:179], v[200:203], v[108:111]
	v_mfma_f32_16x16x32_bf16 v[100:103], v[184:187], v[200:203], v[100:103]
	v_mfma_f32_16x16x32_bf16 v[92:95], v[176:179], v[208:211], v[92:95]
	v_mfma_f32_16x16x32_bf16 v[84:87], v[184:187], v[208:211], v[84:87]
	v_mfma_f32_16x16x32_bf16 v[76:79], v[176:179], v[216:219], v[76:79]
	v_mfma_f32_16x16x32_bf16 v[68:71], v[184:187], v[216:219], v[68:71]
	v_mfma_f32_16x16x32_bf16 v[124:127], v[180:183], v[196:199], v[124:127]
	v_mfma_f32_16x16x32_bf16 v[116:119], v[188:191], v[196:199], v[116:119]
	v_mfma_f32_16x16x32_bf16 v[108:111], v[180:183], v[204:207], v[108:111]
	v_mfma_f32_16x16x32_bf16 v[100:103], v[188:191], v[204:207], v[100:103]
	v_mfma_f32_16x16x32_bf16 v[92:95], v[180:183], v[212:215], v[92:95]
	v_mfma_f32_16x16x32_bf16 v[84:87], v[188:191], v[212:215], v[84:87]
	v_mfma_f32_16x16x32_bf16 v[76:79], v[180:183], v[240:243], v[76:79]
	v_mfma_f32_16x16x32_bf16 v[68:71], v[188:191], v[240:243], v[68:71]
	s_setprio 0
	s_barrier
; __device__ __forceinline__ unsigned cvt_pk_bf16(float lo, float hi) { unsigned r; asm volatile("v_cvt_pk_bf16_f32 %0, %1, %2" : "=v"(r) : "v"(lo), "v"(hi)); return r; }
; __device__ __forceinline__ float siluf_(float x) { return x * sigmoidf_(x); }
; #define PG8_STAGE(bufoff, gbase, voff) do { _Pragma("unroll") for (int _i = 0; _i < 2; ++_i) \
;         __builtin_amdgcn_global_load_lds((const unsigned*)((const char*)(gbase) + (voff)[_i]), (LAS unsigned*)(lds + (bufoff) + ldsw + _i * 8192), 16, 0, 0); } while (0)
; #define PG8_LDA(dst, b, h) do { _Pragma("unroll") for (int m = 0; m < 4; ++m) _Pragma("unroll") for (int k = 0; k < 2; ++k) dst[m][k] = *(const LAS bf16x8*)(lds + PG8_SA(b, h) + aoff + m * 2048 + k * 1024); } while (0)
; #define PG8_WAIT_V(n) asm volatile("s_waitcnt vmcnt(" #n ")" ::: "memory")
; #define PG8_WAIT_L(n) asm volatile("s_waitcnt lgkmcnt(" #n ")" ::: "memory")
; #define PG8_BAR __builtin_amdgcn_s_barrier()
; #define PG8_SCHED __builtin_amdgcn_sched_barrier(0)
;     __device__ __forceinline__ void operator()(const f32x4 (&acc)[2][2][4][2], const Unit& u, int wr, int wc, int fr, int fq) const {
;         const int row0 = u.pm * BM + wr * 64 + fr, col0 = u.pn * HALF + wc * 32 + 8 * fq;
;         float rsv[2][4]; load_rstd(rsv, ssq, row0);
; #pragma unroll
;         for (int ai = 0; ai < 2; ++ai)
; #pragma unroll
;             for (int m = 0; m < 4; ++m) { const int row = row0 + ai * HALF + m * 16; bf16_t* rowp = O + (size_t)row * ldc + col0; const float rs = rsv[ai][m];
;                 f32x4 v0, v1;
; #pragma unroll
;                 for (int j = 0; j < 4; ++j) { v0[j] = siluf_(acc[ai][0][m][0][j] * rs) * (acc[ai][1][m][0][j] * rs); v1[j] = siluf_(acc[ai][0][m][1][j] * rs) * (acc[ai][1][m][1][j] * rs); }
;                 u32x4 w; w.x = cvt_pk_bf16(v0[0], v0[1]); w.y = cvt_pk_bf16(v0[2], v0[3]); w.z = cvt_pk_bf16(v1[0], v1[1]); w.w = cvt_pk_bf16(v1[2], v1[3]);
;                 *(u32x4*)rowp = w; }
; template <class Epi, bool ALIGN_EPI>
; __device__ __forceinline__ void gemm_phase(LAS unsigned char* lds, const Gemm g, const StaticOrder& S, const Epi& E, const int tid) {
;     ...
;             PG8_LDA(At, 1, 1); PG8_STAGE(PG8_SB(1, 0), b3, voffB); PG8_STAGE(PG8_SB(1, 1), b3 + hB, voffB); PG8_STAGE(PG8_SA(1, 0), a3, voffA);
;             PG8_WAIT_V(8); PG8_WAIT_L(0); PG8_BAR; PG8_MMA(1, 0, At, B0); PG8_MMA(1, 1, At, B1); PG8_BAR; PG8_SCHED;
	s_add_i32 s10, s10, s45
	v_lshl_add_u64 v[166:167], v[226:227], 0, s[92:93]
	s_mov_b32 m0, s10
	ds_read_b128 v[192:195], v153 offset:49152
	ds_read_b128 v[196:199], v153 offset:50176
	ds_read_b128 v[200:203], v153 offset:51200
	ds_read_b128 v[204:207], v153 offset:52224
	ds_read_b128 v[208:211], v153 offset:53248
	ds_read_b128 v[212:215], v153 offset:54272
	ds_read_b128 v[216:219], v153 offset:55296
	ds_read_b128 v[240:243], v153 offset:56320
	global_load_lds_dwordx4 v[166:167], off
	v_lshl_add_u64 v[166:167], v[244:245], 0, s[92:93]
	s_add_i32 m0, s10, 0x2000
	s_add_i32 s10, s65, s45
	global_load_lds_dwordx4 v[166:167], off
	v_lshl_add_u64 v[166:167], v[246:247], 0, s[92:93]
	s_mov_b32 m0, s10
	s_nop 0
	global_load_lds_dwordx4 v[166:167], off
	v_lshl_add_u64 v[166:167], v[220:221], 0, s[92:93]
	s_add_i32 m0, s10, 0x2000
	s_nop 0
	global_load_lds_dwordx4 v[166:167], off
	v_lshl_add_u64 v[166:167], v[248:249], 0, s[92:93]
	s_mov_b32 m0, s56
	s_nop 0
	global_load_lds_dwordx4 v[166:167], off
	v_lshl_add_u64 v[166:167], v[250:251], 0, s[92:93]
	s_mov_b32 m0, s57
	s_nop 0
	global_load_lds_dwordx4 v[166:167], off
	s_waitcnt vmcnt(8)
	s_waitcnt lgkmcnt(0)
	s_barrier
	s_setprio 1
	s_waitcnt lgkmcnt(0)
	v_mfma_f32_16x16x32_bf16 v[56:59], v[146:149], v[192:195], v[56:59]
	v_lshrrev_b32_e32 v171, 8, v170
	v_and_b32_e32 v234, 15, v170
	v_lshl_add_u32 v171, v171, 6, v234
	s_lshl_b32 s98, s64, 8
	v_add_u32_e32 v171, s98, v171
	v_mul_lo_u32 v171, v171, s28
	v_bfe_u32 v234, v170, 6, 2
	v_bfe_u32 v224, v170, 4, 2
	v_lshlrev_b32_e32 v234, 5, v234
	v_lshl_or_b32 v234, v224, 3, v234
	v_mfma_f32_16x16x32_bf16 v[48:51], v[158:161], v[192:195], v[48:51]
	s_lshl_b32 s98, s63, 7
	v_add_u32_e32 v234, s98, v234
	v_add_lshl_u32 v232, v171, v234, 1
	v_mov_b32_e32 v233, 0
	v_lshl_add_u64 v[232:233], v[232:233], 0, s[30:31]
	s_lshl_b32 s98, s28, 5
	s_mov_b32 s99, 0
	s_mov_b32 s100, 0xbfb8aa3b
	s_mov_b32 s101, 0xbfb8aa3b
	v_mul_f32_e32 v120, v172, v120
	v_mfma_f32_16x16x32_bf16 v[40:43], v[146:149], v[200:203], v[40:43]
	v_mul_f32_e32 v121, v172, v121
	v_mul_f32_e32 v122, v172, v122
	v_mul_f32_e32 v123, v172, v123
	v_mul_f32_e32 v124, v172, v124
	v_mul_f32_e32 v125, v172, v125
	v_mul_f32_e32 v126, v172, v126
	v_mul_f32_e32 v127, v172, v127
	v_mul_f32_e32 v224, s100, v120
	v_mul_f32_e32 v225, s101, v121
	v_mul_f32_e32 v228, s100, v122
	v_mfma_f32_16x16x32_bf16 v[32:35], v[158:161], v[200:203], v[32:35]
	v_mul_f32_e32 v229, s101, v123
	v_exp_f32_e32 v224, v224
	v_exp_f32_e32 v225, v225
	v_exp_f32_e32 v228, v228
	v_exp_f32_e32 v229, v229
	v_add_f32_e32 v224, 1.0, v224
	v_add_f32_e32 v225, 1.0, v225
	v_add_f32_e32 v228, 1.0, v228
	v_add_f32_e32 v229, 1.0, v229
	v_rcp_f32_e32 v224, v224
	v_mfma_f32_16x16x32_bf16 v[24:27], v[146:149], v[208:211], v[24:27]
	v_rcp_f32_e32 v225, v225
	v_rcp_f32_e32 v228, v228
	v_rcp_f32_e32 v229, v229
	v_nop
	v_mul_f32_e32 v120, v224, v120
	v_mul_f32_e32 v121, v225, v121
	v_mul_f32_e32 v122, v228, v122
	v_mul_f32_e32 v123, v229, v123
	v_mul_f32_e32 v120, v124, v120
	v_mul_f32_e32 v121, v125, v121
	v_mfma_f32_16x16x32_bf16 v[16:19], v[158:161], v[208:211], v[16:19]
	v_mul_f32_e32 v122, v126, v122
	v_mul_f32_e32 v123, v127, v123
	v_mul_f32_e32 v112, v172, v112
	v_mul_f32_e32 v113, v172, v113
	v_mul_f32_e32 v114, v172, v114
	v_mul_f32_e32 v115, v172, v115
	v_mul_f32_e32 v116, v172, v116
	v_mul_f32_e32 v117, v172, v117
	v_mul_f32_e32 v118, v172, v118
	v_mul_f32_e32 v119, v172, v119
	v_mfma_f32_16x16x32_bf16 v[8:11], v[146:149], v[216:219], v[8:11]
	v_mul_f32_e32 v224, s100, v112
	v_mul_f32_e32 v225, s101, v113
	v_mul_f32_e32 v228, s100, v114
	v_mul_f32_e32 v229, s101, v115
	v_exp_f32_e32 v224, v224
	v_exp_f32_e32 v225, v225
	v_exp_f32_e32 v228, v228
	v_exp_f32_e32 v229, v229
	v_add_f32_e32 v224, 1.0, v224
	v_add_f32_e32 v225, 1.0, v225
	v_mfma_f32_16x16x32_bf16 v[4:7], v[158:161], v[216:219], v[4:7]
	v_add_f32_e32 v228, 1.0, v228
	v_add_f32_e32 v229, 1.0, v229
	v_rcp_f32_e32 v224, v224
	v_rcp_f32_e32 v225, v225
	v_rcp_f32_e32 v228, v228
	v_rcp_f32_e32 v229, v229
	v_nop
	v_mul_f32_e32 v112, v224, v112
	v_mul_f32_e32 v113, v225, v113
	v_mul_f32_e32 v114, v228, v114
	v_mfma_f32_16x16x32_bf16 v[56:59], v[154:157], v[196:199], v[56:59]
	v_mul_f32_e32 v115, v229, v115
	v_mul_f32_e32 v112, v116, v112
	v_mul_f32_e32 v113, v117, v113
	v_mul_f32_e32 v114, v118, v114
	v_mul_f32_e32 v115, v119, v115
	v_cvt_pk_bf16_f32 v120, v120, v121
	v_cvt_pk_bf16_f32 v121, v122, v123
	v_cvt_pk_bf16_f32 v122, v112, v113
	v_cvt_pk_bf16_f32 v123, v114, v115
	global_store_dwordx4 v[232:233], v[120:123], off
	v_mfma_f32_16x16x32_bf16 v[48:51], v[162:165], v[196:199], v[48:51]
	v_lshl_add_u64 v[232:233], v[232:233], 0, s[98:99]
	v_mul_f32_e32 v104, v173, v104
	v_mul_f32_e32 v105, v173, v105
	v_mul_f32_e32 v106, v173, v106
	v_mul_f32_e32 v107, v173, v107
	v_mul_f32_e32 v108, v173, v108
	v_mul_f32_e32 v109, v173, v109
	v_mul_f32_e32 v110, v173, v110
	v_mul_f32_e32 v111, v173, v111
	v_mul_f32_e32 v224, s100, v104
	v_mfma_f32_16x16x32_bf16 v[40:43], v[154:157], v[204:207], v[40:43]
	v_mul_f32_e32 v225, s101, v105
	v_mul_f32_e32 v228, s100, v106
	v_mul_f32_e32 v229, s101, v107
	v_exp_f32_e32 v224, v224
	v_exp_f32_e32 v225, v225
	v_exp_f32_e32 v228, v228
	v_exp_f32_e32 v229, v229
	v_add_f32_e32 v224, 1.0, v224
	v_add_f32_e32 v225, 1.0, v225
	v_add_f32_e32 v228, 1.0, v228
	v_mfma_f32_16x16x32_bf16 v[32:35], v[162:165], v[204:207], v[32:35]
	v_add_f32_e32 v229, 1.0, v229
	v_rcp_f32_e32 v224, v224
	v_rcp_f32_e32 v225, v225
	v_rcp_f32_e32 v228, v228
	v_rcp_f32_e32 v229, v229
	v_nop
	v_mul_f32_e32 v104, v224, v104
	v_mul_f32_e32 v105, v225, v105
	v_mul_f32_e32 v106, v228, v106
; __device__ __forceinline__ unsigned cvt_pk_bf16(float lo, float hi) { unsigned r; asm volatile("v_cvt_pk_bf16_f32 %0, %1, %2" : "=v"(r) : "v"(lo), "v"(hi)); return r; }
; __device__ __forceinline__ float siluf_(float x) { return x * sigmoidf_(x); }
;     __device__ __forceinline__ void operator()(const f32x4 (&acc)[2][2][4][2], const Unit& u, int wr, int wc, int fr, int fq) const {
;         const int row0 = u.pm * BM + wr * 64 + fr, col0 = u.pn * HALF + wc * 32 + 8 * fq;
;         float rsv[2][4]; load_rstd(rsv, ssq, row0);
; #pragma unroll
;         for (int ai = 0; ai < 2; ++ai)
; #pragma unroll
;             for (int m = 0; m < 4; ++m) { const int row = row0 + ai * HALF + m * 16; bf16_t* rowp = O + (size_t)row * ldc + col0; const float rs = rsv[ai][m];
;                 f32x4 v0, v1;
; #pragma unroll
;                 for (int j = 0; j < 4; ++j) { v0[j] = siluf_(acc[ai][0][m][0][j] * rs) * (acc[ai][1][m][0][j] * rs); v1[j] = siluf_(acc[ai][0][m][1][j] * rs) * (acc[ai][1][m][1][j] * rs); }
;                 u32x4 w; w.x = cvt_pk_bf16(v0[0], v0[1]); w.y = cvt_pk_bf16(v0[2], v0[3]); w.z = cvt_pk_bf16(v1[0], v1[1]); w.w = cvt_pk_bf16(v1[2], v1[3]);
;                 *(u32x4*)rowp = w; }
	v_mul_f32_e32 v107, v229, v107
	v_mfma_f32_16x16x32_bf16 v[24:27], v[154:157], v[212:215], v[24:27]
	v_mul_f32_e32 v104, v108, v104
	v_mul_f32_e32 v105, v109, v105
	v_mul_f32_e32 v106, v110, v106
	v_mul_f32_e32 v107, v111, v107
	v_mul_f32_e32 v96, v173, v96
	v_mul_f32_e32 v97, v173, v97
	v_mul_f32_e32 v98, v173, v98
	v_mul_f32_e32 v99, v173, v99
	v_mul_f32_e32 v100, v173, v100
	v_mul_f32_e32 v101, v173, v101
	v_mfma_f32_16x16x32_bf16 v[16:19], v[162:165], v[212:215], v[16:19]
	v_mul_f32_e32 v102, v173, v102
	v_mul_f32_e32 v103, v173, v103
	v_mul_f32_e32 v224, s100, v96
	v_mul_f32_e32 v225, s101, v97
	v_mul_f32_e32 v228, s100, v98
	v_mul_f32_e32 v229, s101, v99
	v_exp_f32_e32 v224, v224
	v_exp_f32_e32 v225, v225
	v_exp_f32_e32 v228, v228
	v_exp_f32_e32 v229, v229
	v_mfma_f32_16x16x32_bf16 v[8:11], v[154:157], v[240:243], v[8:11]
	v_add_f32_e32 v224, 1.0, v224
	v_add_f32_e32 v225, 1.0, v225
	v_add_f32_e32 v228, 1.0, v228
	v_add_f32_e32 v229, 1.0, v229
	v_rcp_f32_e32 v224, v224
	v_rcp_f32_e32 v225, v225
	v_rcp_f32_e32 v228, v228
	v_rcp_f32_e32 v229, v229
	v_nop
	v_mul_f32_e32 v96, v224, v96
	v_mfma_f32_16x16x32_bf16 v[4:7], v[162:165], v[240:243], v[4:7]
	v_mul_f32_e32 v97, v225, v97
	v_mul_f32_e32 v98, v228, v98
	v_mul_f32_e32 v99, v229, v99
	v_mul_f32_e32 v96, v100, v96
	v_mul_f32_e32 v97, v101, v97
	v_mul_f32_e32 v98, v102, v98
	v_mul_f32_e32 v99, v103, v99
	v_cvt_pk_bf16_f32 v104, v104, v105
	v_cvt_pk_bf16_f32 v105, v106, v107
	v_cvt_pk_bf16_f32 v106, v96, v97
	s_setprio 0
	s_setprio 1
	v_mfma_f32_16x16x32_bf16 v[60:63], v[176:179], v[192:195], v[60:63]
	v_cvt_pk_bf16_f32 v107, v98, v99
	global_store_dwordx4 v[232:233], v[104:107], off
	v_lshl_add_u64 v[232:233], v[232:233], 0, s[98:99]
	v_mul_f32_e32 v88, v236, v88
	v_mul_f32_e32 v89, v236, v89
	v_mul_f32_e32 v90, v236, v90
	v_mul_f32_e32 v91, v236, v91
	v_mul_f32_e32 v92, v236, v92
	v_mul_f32_e32 v93, v236, v93
	v_mul_f32_e32 v94, v236, v94
	v_mfma_f32_16x16x32_bf16 v[52:55], v[184:187], v[192:195], v[52:55]
	v_mul_f32_e32 v95, v236, v95
	v_mul_f32_e32 v224, s100, v88
	v_mul_f32_e32 v225, s101, v89
	v_mul_f32_e32 v228, s100, v90
	v_mul_f32_e32 v229, s101, v91
	v_exp_f32_e32 v224, v224
	v_exp_f32_e32 v225, v225
	v_exp_f32_e32 v228, v228
	v_exp_f32_e32 v229, v229
	v_add_f32_e32 v224, 1.0, v224
	v_mfma_f32_16x16x32_bf16 v[44:47], v[176:179], v[200:203], v[44:47]
	v_add_f32_e32 v225, 1.0, v225
	v_add_f32_e32 v228, 1.0, v228
	v_add_f32_e32 v229, 1.0, v229
	v_rcp_f32_e32 v224, v224
	v_rcp_f32_e32 v225, v225
	v_rcp_f32_e32 v228, v228
	v_rcp_f32_e32 v229, v229
	v_nop
	v_mul_f32_e32 v88, v224, v88
	v_mul_f32_e32 v89, v225, v89
	v_mfma_f32_16x16x32_bf16 v[36:39], v[184:187], v[200:203], v[36:39]
	v_mul_f32_e32 v90, v228, v90
	v_mul_f32_e32 v91, v229, v91
	v_mul_f32_e32 v88, v92, v88
	v_mul_f32_e32 v89, v93, v89
	v_mul_f32_e32 v90, v94, v90
	v_mul_f32_e32 v91, v95, v91
	v_mul_f32_e32 v80, v236, v80
	v_mul_f32_e32 v81, v236, v81
	v_mul_f32_e32 v82, v236, v82
	v_mul_f32_e32 v83, v236, v83
	v_mfma_f32_16x16x32_bf16 v[28:31], v[176:179], v[208:211], v[28:31]
	v_mul_f32_e32 v84, v236, v84
	v_mul_f32_e32 v85, v236, v85
	v_mul_f32_e32 v86, v236, v86
	v_mul_f32_e32 v87, v236, v87
	v_mul_f32_e32 v224, s100, v80
	v_mul_f32_e32 v225, s101, v81
	v_mul_f32_e32 v228, s100, v82
	v_mul_f32_e32 v229, s101, v83
	v_exp_f32_e32 v224, v224
	v_exp_f32_e32 v225, v225
	v_mfma_f32_16x16x32_bf16 v[20:23], v[184:187], v[208:211], v[20:23]
	v_exp_f32_e32 v228, v228
	v_exp_f32_e32 v229, v229
	v_add_f32_e32 v224, 1.0, v224
	v_add_f32_e32 v225, 1.0, v225
	v_add_f32_e32 v228, 1.0, v228
	v_add_f32_e32 v229, 1.0, v229
	v_rcp_f32_e32 v224, v224
	v_rcp_f32_e32 v225, v225
;     __device__ __forceinline__ void operator()(const f32x4 (&acc)[2][2][4][2], const Unit& u, int wr, int wc, int fr, int fq) const {
;         const int row0 = u.pm * BM + wr * 64 + fr, col0 = u.pn * HALF + wc * 32 + 8 * fq;
;         float rsv[2][4]; load_rstd(rsv, ssq, row0);
; #pragma unroll
;         for (int ai = 0; ai < 2; ++ai)
; #pragma unroll
;             for (int m = 0; m < 4; ++m) { const int row = row0 + ai * HALF + m * 16; bf16_t* rowp = O + (size_t)row * ldc + col0; const float rs = rsv[ai][m];
;                 f32x4 v0, v1;
; #pragma unroll
;                 for (int j = 0; j < 4; ++j) { v0[j] = siluf_(acc[ai][0][m][0][j] * rs) * (acc[ai][1][m][0][j] * rs); v1[j] = siluf_(acc[ai][0][m][1][j] * rs) * (acc[ai][1][m][1][j] * rs); }
;                 u32x4 w; w.x = cvt_pk_bf16(v0[0], v0[1]); w.y = cvt_pk_bf16(v0[2], v0[3]); w.z = cvt_pk_bf16(v1[0], v1[1]); w.w = cvt_pk_bf16(v1[2], v1[3]);
;                 *(u32x4*)rowp = w; }
; template <class Epi, bool ALIGN_EPI>
; __device__ __forceinline__ void gemm_phase(LAS unsigned char* lds, const Gemm g, const StaticOrder& S, const Epi& E, const int tid) {
;     ...
;         for (int t = 0; t < nt; t += 2) {
;             const bool last = (t == nt - 2);
;             const char* a1 = cA + (size_t)(t + 1) * kstep;
;             const char* a2 = last ? nA : cA + (size_t)(t + 2) * kstep; const char* b2 = last ? nB : cB + (size_t)(t + 2) * kstep;
;             const char* a3 = a2 + kstep; const char* b3 = b2 + kstep;
;             PG8_LDB(B0, 0, 0); PG8_LDB(B1, 0, 1); PG8_SCHED; PG8_LDA(At, 0, 0); PG8_STAGE(PG8_SA(1, 1), a1 + hA, voffA);
;             PG8_WAIT_V(8); PG8_WAIT_L(0); PG8_BAR; PG8_MMA(0, 0, At, B0); PG8_MMA(0, 1, At, B1); PG8_BAR; PG8_SCHED;
;             PG8_LDA(At, 0, 1); PG8_STAGE(PG8_SB(0, 0), b2, voffB); PG8_STAGE(PG8_SB(0, 1), b2 + hB, voffB); PG8_STAGE(PG8_SA(0, 0), a2, voffA);
;             PG8_WAIT_V(8); PG8_WAIT_L(0); PG8_BAR; PG8_MMA(1, 0, At, B0); PG8_MMA(1, 1, At, B1); PG8_BAR; PG8_SCHED;
;             PG8_LDB(B0, 1, 0); PG8_LDB(B1, 1, 1); PG8_SCHED; PG8_LDA(At, 1, 0); PG8_STAGE(PG8_SA(0, 1), a2 + hA, voffA);
;             PG8_WAIT_V(8); PG8_WAIT_L(0); PG8_BAR; PG8_MMA(0, 0, At, B0); PG8_MMA(0, 1, At, B1); PG8_BAR; PG8_SCHED;
;             PG8_LDA(At, 1, 1); PG8_STAGE(PG8_SB(1, 0), b3, voffB); PG8_STAGE(PG8_SB(1, 1), b3 + hB, voffB); PG8_STAGE(PG8_SA(1, 0), a3, voffA);
	v_rcp_f32_e32 v228, v228
	v_rcp_f32_e32 v229, v229
	v_mfma_f32_16x16x32_bf16 v[12:15], v[176:179], v[216:219], v[12:15]
	v_nop
	v_mul_f32_e32 v80, v224, v80
	v_mul_f32_e32 v81, v225, v81
	v_mul_f32_e32 v82, v228, v82
	v_mul_f32_e32 v83, v229, v83
	v_mul_f32_e32 v80, v84, v80
	v_mul_f32_e32 v81, v85, v81
	v_mul_f32_e32 v82, v86, v82
	v_mul_f32_e32 v83, v87, v83
	v_cvt_pk_bf16_f32 v88, v88, v89
	v_mfma_f32_16x16x32_bf16 v[0:3], v[184:187], v[216:219], v[0:3]
	v_cvt_pk_bf16_f32 v89, v90, v91
	v_cvt_pk_bf16_f32 v90, v80, v81
	v_cvt_pk_bf16_f32 v91, v82, v83
	global_store_dwordx4 v[232:233], v[88:91], off
	v_lshl_add_u64 v[232:233], v[232:233], 0, s[98:99]
	v_mul_f32_e32 v72, v237, v72
	v_mul_f32_e32 v73, v237, v73
	v_mul_f32_e32 v74, v237, v74
	v_mul_f32_e32 v75, v237, v75
	v_mul_f32_e32 v76, v237, v76
	v_mfma_f32_16x16x32_bf16 v[60:63], v[180:183], v[196:199], v[60:63]
	v_mul_f32_e32 v77, v237, v77
	v_mul_f32_e32 v78, v237, v78
	v_mul_f32_e32 v79, v237, v79
	v_mul_f32_e32 v224, s100, v72
	v_mul_f32_e32 v225, s101, v73
	v_mul_f32_e32 v228, s100, v74
	v_mul_f32_e32 v229, s101, v75
	v_exp_f32_e32 v224, v224
	v_exp_f32_e32 v225, v225
	v_exp_f32_e32 v228, v228
	v_mfma_f32_16x16x32_bf16 v[52:55], v[188:191], v[196:199], v[52:55]
	v_exp_f32_e32 v229, v229
	v_add_f32_e32 v224, 1.0, v224
	v_add_f32_e32 v225, 1.0, v225
	v_add_f32_e32 v228, 1.0, v228
	v_add_f32_e32 v229, 1.0, v229
	v_rcp_f32_e32 v224, v224
	v_rcp_f32_e32 v225, v225
	v_rcp_f32_e32 v228, v228
	v_rcp_f32_e32 v229, v229
	v_nop
	v_mfma_f32_16x16x32_bf16 v[44:47], v[180:183], v[204:207], v[44:47]
	v_mul_f32_e32 v72, v224, v72
	v_mul_f32_e32 v73, v225, v73
	v_mul_f32_e32 v74, v228, v74
	v_mul_f32_e32 v75, v229, v75
	v_mul_f32_e32 v72, v76, v72
	v_mul_f32_e32 v73, v77, v73
	v_mul_f32_e32 v74, v78, v74
	v_mul_f32_e32 v75, v79, v75
	v_mul_f32_e32 v64, v237, v64
	v_mul_f32_e32 v65, v237, v65
	v_mfma_f32_16x16x32_bf16 v[36:39], v[188:191], v[204:207], v[36:39]
	v_mul_f32_e32 v66, v237, v66
	v_mul_f32_e32 v67, v237, v67
	v_mul_f32_e32 v68, v237, v68
	v_mul_f32_e32 v69, v237, v69
	v_mul_f32_e32 v70, v237, v70
	v_mul_f32_e32 v71, v237, v71
	v_mul_f32_e32 v224, s100, v64
	v_mul_f32_e32 v225, s101, v65
	v_mul_f32_e32 v228, s100, v66
	v_mul_f32_e32 v229, s101, v67
	v_mfma_f32_16x16x32_bf16 v[28:31], v[180:183], v[212:215], v[28:31]
	v_exp_f32_e32 v224, v224
	v_exp_f32_e32 v225, v225
	v_exp_f32_e32 v228, v228
	v_exp_f32_e32 v229, v229
	v_add_f32_e32 v224, 1.0, v224
	v_add_f32_e32 v225, 1.0, v225
	v_add_f32_e32 v228, 1.0, v228
	v_add_f32_e32 v229, 1.0, v229
	v_rcp_f32_e32 v224, v224
	v_rcp_f32_e32 v225, v225
	v_mfma_f32_16x16x32_bf16 v[20:23], v[188:191], v[212:215], v[20:23]
	v_rcp_f32_e32 v228, v228
	v_rcp_f32_e32 v229, v229
	v_nop
	v_mul_f32_e32 v64, v224, v64
	v_mul_f32_e32 v65, v225, v65
	v_mul_f32_e32 v66, v228, v66
	v_mul_f32_e32 v67, v229, v67
	v_mul_f32_e32 v64, v68, v64
	v_mul_f32_e32 v65, v69, v65
	v_mul_f32_e32 v66, v70, v66
	v_mfma_f32_16x16x32_bf16 v[12:15], v[180:183], v[240:243], v[12:15]
	v_mul_f32_e32 v67, v71, v67
	v_cvt_pk_bf16_f32 v72, v72, v73
	v_cvt_pk_bf16_f32 v73, v74, v75
	v_cvt_pk_bf16_f32 v74, v64, v65
	v_cvt_pk_bf16_f32 v75, v66, v67
	global_store_dwordx4 v[232:233], v[72:75], off
	v_lshl_add_u64 v[232:233], v[232:233], 0, s[98:99]
	v_lshl_add_u64 v[232:233], v[232:233], 0, s[98:99]
	v_lshl_add_u64 v[232:233], v[232:233], 0, s[98:99]
	v_lshl_add_u64 v[232:233], v[232:233], 0, s[98:99]
	v_mfma_f32_16x16x32_bf16 v[0:3], v[188:191], v[240:243], v[0:3]
	v_lshl_add_u64 v[232:233], v[232:233], 0, s[98:99]
	s_setprio 0
	s_barrier
	v_lshl_add_u64 v[142:143], v[142:143], 0, s[80:81]
	v_lshl_add_u64 v[144:145], v[144:145], 0, s[80:81]
